# k2/k9 step loops: canonicalising v_max(x,x) before row-max ops folded away (5 VALU per step)
# baseline (speedup 1.0000x reference)
.LBB2_50:
	s_nop 9
	v_max_f32_e32 v98, v34, v50
	v_max3_f32 v98, v98, v35, v36
	v_max3_f32 v98, v98, v37, v38
	v_max3_f32 v98, v98, v39, v40
	v_max3_f32 v98, v98, v41, v42
	v_max3_f32 v98, v98, v43, v44
	v_max3_f32 v98, v98, v45, v46
	v_max3_f32 v98, v98, v47, v48
	v_max3_f32 v98, v98, v49, v51
	v_max3_f32 v98, v98, v52, v53
	v_max3_f32 v98, v98, v54, v55
	v_max3_f32 v98, v98, v56, v57
	v_max3_f32 v98, v98, v58, v59
	v_max3_f32 v98, v98, v60, v61
	v_max3_f32 v98, v98, v62, v63
	v_max3_f32 v98, v98, v64, v65
	v_mov_b32_e32 v100, v98
	s_nop 1
	v_permlane32_swap_b32_e32 v98, v100
	v_max_f32_e32 v100, v98, v100
	s_and_b64 vcc, exec, s[0:1]
	s_cbranch_vccz .LBB2_93
	v_cmp_lt_f32_e32 vcc, s80, v100
	s_mov_b64 s[82:83], 0
	s_mov_b64 s[0:1], 0
	s_cbranch_vccz .LBB2_53
	v_max_f32_e32 v98, 0, v100
	s_mov_b64 s[0:1], -1

.LBB2_130:
	s_xor_b64 s[0:1], s[12:13], -1
	s_waitcnt lgkmcnt(7)
	v_mfma_f32_32x32x16_bf16 v[66:81], v[174:177], v[102:105], v[66:81]
	s_waitcnt lgkmcnt(5)
	v_mfma_f32_32x32x16_bf16 v[82:97], v[178:181], v[102:105], v[82:97]
	v_mfma_f32_32x32x16_bf16 v[66:81], v[158:161], v[106:109], v[66:81]
	s_waitcnt lgkmcnt(4)
	v_mfma_f32_32x32x16_bf16 v[82:97], v[162:165], v[106:109], v[82:97]
	s_waitcnt lgkmcnt(3)
	v_mfma_f32_32x32x16_bf16 v[66:81], v[154:157], v[110:113], v[66:81]
	s_waitcnt lgkmcnt(1)
	v_mfma_f32_32x32x16_bf16 v[82:97], v[170:173], v[110:113], v[82:97]
	v_mfma_f32_32x32x16_bf16 v[66:81], v[150:153], v[114:117], v[66:81]
	ds_read_b64_tr_b16 v[162:163], v247 offset:34816
	ds_read_b64_tr_b16 v[158:159], v247 offset:34880
	ds_read_b64_tr_b16 v[154:155], v247 offset:34944
	ds_read_b64_tr_b16 v[150:151], v247 offset:35008
	ds_read_b64_tr_b16 v[164:165], v247 offset:37376
	ds_read_b64_tr_b16 v[160:161], v247 offset:37440
	ds_read_b64_tr_b16 v[156:157], v247 offset:37504
	ds_read_b64_tr_b16 v[152:153], v247 offset:37568
	s_waitcnt lgkmcnt(8)
	v_mfma_f32_32x32x16_bf16 v[82:97], v[166:169], v[114:117], v[82:97]
	s_nop 11
	v_max_f32_e32 v98, v66, v82
	v_max3_f32 v98, v98, v67, v68
	v_max3_f32 v98, v98, v69, v70
	v_max3_f32 v98, v98, v71, v72
	v_max3_f32 v98, v98, v73, v74
	v_max3_f32 v98, v98, v75, v76
	v_max3_f32 v98, v98, v77, v78
	v_max3_f32 v98, v98, v79, v80
	v_max3_f32 v98, v98, v81, v83
	v_max3_f32 v98, v98, v84, v85
	v_max3_f32 v98, v98, v86, v87
	v_max3_f32 v98, v98, v88, v89
	v_max3_f32 v98, v98, v90, v91
	v_max3_f32 v98, v98, v92, v93
	v_max3_f32 v98, v98, v94, v95
	v_max3_f32 v98, v98, v96, v97
	v_mov_b32_e32 v100, v98
	s_nop 1
	v_permlane32_swap_b32_e32 v98, v100
	v_max_f32_e32 v100, v98, v100
	s_and_b64 vcc, exec, s[0:1]
	s_cbranch_vccz .LBB2_167
	v_cmp_lt_f32_e32 vcc, s80, v100
	s_mov_b64 s[14:15], 0
	s_mov_b64 s[0:1], 0
	s_cbranch_vccz .LBB2_133
	v_max_f32_e32 v98, 0, v100
	s_mov_b64 s[0:1], -1

.LBB2_152:
	s_waitcnt lgkmcnt(7)
	v_mfma_f32_32x32x16_bf16 v[66:81], v[174:177], v[102:105], v[66:81]
	s_waitcnt lgkmcnt(5)
	v_mfma_f32_32x32x16_bf16 v[82:97], v[178:181], v[102:105], v[82:97]
	v_mfma_f32_32x32x16_bf16 v[66:81], v[158:161], v[106:109], v[66:81]
	s_waitcnt lgkmcnt(4)
	v_mfma_f32_32x32x16_bf16 v[82:97], v[162:165], v[106:109], v[82:97]
	s_waitcnt lgkmcnt(3)
	v_mfma_f32_32x32x16_bf16 v[66:81], v[154:157], v[110:113], v[66:81]
	s_waitcnt lgkmcnt(1)
	v_mfma_f32_32x32x16_bf16 v[82:97], v[170:173], v[110:113], v[82:97]
	v_mfma_f32_32x32x16_bf16 v[66:81], v[150:153], v[114:117], v[66:81]
	ds_read_b64_tr_b16 v[162:163], v247 offset:55296
	ds_read_b64_tr_b16 v[158:159], v247 offset:55360
	ds_read_b64_tr_b16 v[154:155], v247 offset:55424
	ds_read_b64_tr_b16 v[150:151], v247 offset:55488
	ds_read_b64_tr_b16 v[164:165], v247 offset:57856
	ds_read_b64_tr_b16 v[160:161], v247 offset:57920
	ds_read_b64_tr_b16 v[156:157], v247 offset:57984
	ds_read_b64_tr_b16 v[152:153], v247 offset:58048
	s_waitcnt lgkmcnt(8)
	v_mfma_f32_32x32x16_bf16 v[82:97], v[166:169], v[114:117], v[82:97]
	s_nop 11
	v_max_f32_e32 v98, v66, v82
	v_max3_f32 v98, v98, v67, v68
	v_max3_f32 v98, v98, v69, v70
	v_max3_f32 v98, v98, v71, v72
	v_max3_f32 v98, v98, v73, v74
	v_max3_f32 v98, v98, v75, v76
	v_max3_f32 v98, v98, v77, v78
	v_max3_f32 v98, v98, v79, v80
	v_max3_f32 v98, v98, v81, v83
	v_max3_f32 v98, v98, v84, v85
	v_max3_f32 v98, v98, v86, v87
	v_max3_f32 v98, v98, v88, v89
	v_max3_f32 v98, v98, v90, v91
	v_max3_f32 v98, v98, v92, v93
	v_max3_f32 v98, v98, v94, v95
	v_max3_f32 v98, v98, v96, v97
	v_mov_b32_e32 v100, v98
	s_nop 1
	v_permlane32_swap_b32_e32 v98, v100
	v_max_f32_e32 v100, v98, v100
	s_and_b64 vcc, exec, s[0:1]
	s_cbranch_vccz .LBB2_168
	v_cmp_lt_f32_e32 vcc, s80, v100
	s_mov_b64 s[14:15], 0
	s_mov_b64 s[0:1], 0
	s_cbranch_vccz .LBB2_155
	v_max_f32_e32 v98, 0, v100
	s_mov_b64 s[0:1], -1

.LBB9_40:
	s_add_i32 s67, s63, s66
	s_cmp_le_i32 s67, s45
	s_cselect_b64 s[38:39], -1, 0
	s_and_b64 s[38:39], s[4:5], s[38:39]
	s_cmp_ge_i32 s67, s46
	s_cselect_b64 s[40:41], -1, 0
	s_and_b64 s[38:39], s[38:39], s[40:41]
	s_andn2_b64 vcc, exec, s[38:39]
	s_cbranch_vccnz .LBB9_49
	v_add_u32_e32 v36, v35, v128
	v_add_u32_e32 v66, s47, v144
	ds_read_b128 v[120:123], v36
	ds_read_b128 v[124:127], v36 offset:32
	ds_read_b128 v[146:149], v36 offset:8704
	ds_read_b128 v[150:153], v36 offset:8736
	ds_read_b128 v[154:157], v36 offset:64
	ds_read_b128 v[158:161], v36 offset:96
	ds_read_b128 v[162:165], v36 offset:8768
	ds_read_b128 v[166:169], v36 offset:8800
	v_add_u32_e32 v70, 0x12c10, v66
	ds_read2_b32 v[36:37], v70 offset0:59 offset1:58
	ds_read2_b32 v[38:39], v70 offset0:57 offset1:56
	ds_read2_b32 v[40:41], v70 offset0:51 offset1:50
	ds_read2_b32 v[42:43], v70 offset0:49 offset1:48
	ds_read2_b32 v[44:45], v70 offset0:43 offset1:42
	ds_read2_b32 v[46:47], v70 offset0:41 offset1:40
	ds_read2_b32 v[48:49], v70 offset0:35 offset1:34
	ds_read2_b32 v[50:51], v70 offset0:33 offset1:32
	ds_read2_b32 v[52:53], v70 offset0:27 offset1:26
	ds_read2_b32 v[54:55], v70 offset0:25 offset1:24
	ds_read2_b32 v[56:57], v70 offset0:19 offset1:18
	ds_read2_b32 v[58:59], v70 offset0:17 offset1:16
	ds_read2_b32 v[60:61], v70 offset0:11 offset1:10
	ds_read2_b32 v[62:63], v70 offset0:9 offset1:8
	ds_read2_b32 v[64:65], v70 offset0:3 offset1:2
	ds_read2_b32 v[66:67], v70 offset0:1 offset1:0
	s_waitcnt lgkmcnt(15)
	v_pk_add_f32 v[36:37], v[36:37], v[138:139] op_sel_hi:[1,0] neg_lo:[0,1] neg_hi:[0,1]
	s_waitcnt lgkmcnt(14)
	v_pk_add_f32 v[38:39], v[38:39], v[138:139] op_sel_hi:[1,0] neg_lo:[0,1] neg_hi:[0,1]
	s_waitcnt lgkmcnt(13)
	v_pk_add_f32 v[40:41], v[40:41], v[138:139] op_sel_hi:[1,0] neg_lo:[0,1] neg_hi:[0,1]
	s_waitcnt lgkmcnt(12)
	v_pk_add_f32 v[42:43], v[42:43], v[138:139] op_sel_hi:[1,0] neg_lo:[0,1] neg_hi:[0,1]
	s_waitcnt lgkmcnt(11)
	v_pk_add_f32 v[44:45], v[44:45], v[138:139] op_sel_hi:[1,0] neg_lo:[0,1] neg_hi:[0,1]
	s_waitcnt lgkmcnt(10)
	v_pk_add_f32 v[46:47], v[46:47], v[138:139] op_sel_hi:[1,0] neg_lo:[0,1] neg_hi:[0,1]
	s_waitcnt lgkmcnt(9)
	v_pk_add_f32 v[48:49], v[48:49], v[138:139] op_sel_hi:[1,0] neg_lo:[0,1] neg_hi:[0,1]
	s_waitcnt lgkmcnt(8)
	v_pk_add_f32 v[50:51], v[50:51], v[138:139] op_sel_hi:[1,0] neg_lo:[0,1] neg_hi:[0,1]
	s_waitcnt lgkmcnt(7)
	v_pk_add_f32 v[52:53], v[52:53], v[138:139] op_sel_hi:[1,0] neg_lo:[0,1] neg_hi:[0,1]
	s_waitcnt lgkmcnt(6)
	v_pk_add_f32 v[54:55], v[54:55], v[138:139] op_sel_hi:[1,0] neg_lo:[0,1] neg_hi:[0,1]
	s_waitcnt lgkmcnt(5)
	v_pk_add_f32 v[56:57], v[56:57], v[138:139] op_sel_hi:[1,0] neg_lo:[0,1] neg_hi:[0,1]
	s_waitcnt lgkmcnt(4)
	v_pk_add_f32 v[58:59], v[58:59], v[138:139] op_sel_hi:[1,0] neg_lo:[0,1] neg_hi:[0,1]
	s_waitcnt lgkmcnt(3)
	v_pk_add_f32 v[60:61], v[60:61], v[138:139] op_sel_hi:[1,0] neg_lo:[0,1] neg_hi:[0,1]
	s_waitcnt lgkmcnt(2)
	v_pk_add_f32 v[62:63], v[62:63], v[138:139] op_sel_hi:[1,0] neg_lo:[0,1] neg_hi:[0,1]
	s_waitcnt lgkmcnt(1)
	v_pk_add_f32 v[64:65], v[64:65], v[138:139] op_sel_hi:[1,0] neg_lo:[0,1] neg_hi:[0,1]
	s_waitcnt lgkmcnt(0)
	v_pk_add_f32 v[66:67], v[66:67], v[138:139] op_sel_hi:[1,0] neg_lo:[0,1] neg_hi:[0,1]
	s_xor_b64 s[38:39], s[12:13], -1
	v_mfma_f32_32x32x16_bf16 v[36:51], v[120:123], v[72:75], v[36:51]
	v_mfma_f32_32x32x16_bf16 v[52:67], v[146:149], v[72:75], v[52:67]
	v_mfma_f32_32x32x16_bf16 v[36:51], v[124:127], v[76:79], v[36:51]
	ds_read_b64_tr_b16 v[124:125], v129 offset:34816
	ds_read_b64_tr_b16 v[126:127], v129 offset:37376
	ds_read_b64_tr_b16 v[122:123], v129 offset:37440
	ds_read_b64_tr_b16 v[120:121], v129 offset:34880
	v_mfma_f32_32x32x16_bf16 v[52:67], v[150:153], v[76:79], v[52:67]
	v_mfma_f32_32x32x16_bf16 v[36:51], v[154:157], v[80:83], v[36:51]
	v_mfma_f32_32x32x16_bf16 v[52:67], v[162:165], v[80:83], v[52:67]
	v_mfma_f32_32x32x16_bf16 v[36:51], v[158:161], v[84:87], v[36:51]
	v_mfma_f32_32x32x16_bf16 v[52:67], v[166:169], v[84:87], v[52:67]
	s_nop 11
	v_max_f32_e32 v68, v36, v52
	v_max3_f32 v68, v68, v37, v38
	v_max3_f32 v68, v68, v39, v40
	v_max3_f32 v68, v68, v41, v42
	v_max3_f32 v68, v68, v43, v44
	v_max3_f32 v68, v68, v45, v46
	v_max3_f32 v68, v68, v47, v48
	v_max3_f32 v68, v68, v49, v50
	v_max3_f32 v68, v68, v51, v53
	v_max3_f32 v68, v68, v54, v55
	v_max3_f32 v68, v68, v56, v57
	v_max3_f32 v68, v68, v58, v59
	v_max3_f32 v68, v68, v60, v61
	v_max3_f32 v68, v68, v62, v63
	v_max3_f32 v68, v68, v64, v65
	v_max3_f32 v68, v68, v66, v67
	v_mov_b32_e32 v70, v68
	s_nop 1
	v_permlane32_swap_b32_e32 v68, v70
	v_max_f32_e32 v70, v68, v70
	s_and_b64 vcc, exec, s[38:39]
	s_cbranch_vccz .LBB9_75
	v_cmp_lt_f32_e32 vcc, s57, v70
	s_mov_b64 s[40:41], 0
	s_mov_b64 s[38:39], 0
	s_cbranch_vccz .LBB9_44
	v_max_f32_e32 v68, 0, v70
	s_mov_b64 s[38:39], -1

.LBB9_59:
	s_add_i32 s67, s67, 1
	s_cmp_le_i32 s67, s45
	s_cselect_b64 s[40:41], -1, 0
	s_and_b64 s[40:41], s[4:5], s[40:41]
	s_cmp_ge_i32 s67, s46
	s_cselect_b64 s[66:67], -1, 0
	s_and_b64 s[40:41], s[40:41], s[66:67]
	s_andn2_b64 vcc, exec, s[40:41]
	s_cbranch_vccnz .LBB9_68
	v_add_u32_e32 v36, v35, v128
	v_add_u32_e32 v66, s62, v143
	ds_read_b128 v[120:123], v36 offset:17408
	ds_read_b128 v[124:127], v36 offset:17440
	ds_read_b128 v[146:149], v36 offset:26112
	ds_read_b128 v[150:153], v36 offset:26144
	ds_read_b128 v[154:157], v36 offset:17472
	ds_read_b128 v[158:161], v36 offset:17504
	ds_read_b128 v[162:165], v36 offset:26176
	ds_read_b128 v[166:169], v36 offset:26208
	v_add_u32_e32 v70, 0x12b10, v66
	ds_read2_b32 v[36:37], v70 offset0:59 offset1:58
	ds_read2_b32 v[38:39], v70 offset0:57 offset1:56
	ds_read2_b32 v[40:41], v70 offset0:51 offset1:50
	ds_read2_b32 v[42:43], v70 offset0:49 offset1:48
	ds_read2_b32 v[44:45], v70 offset0:43 offset1:42
	ds_read2_b32 v[46:47], v70 offset0:41 offset1:40
	ds_read2_b32 v[48:49], v70 offset0:35 offset1:34
	ds_read2_b32 v[50:51], v70 offset0:33 offset1:32
	ds_read2_b32 v[52:53], v70 offset0:27 offset1:26
	ds_read2_b32 v[54:55], v70 offset0:25 offset1:24
	ds_read2_b32 v[56:57], v70 offset0:19 offset1:18
	ds_read2_b32 v[58:59], v70 offset0:17 offset1:16
	ds_read2_b32 v[60:61], v70 offset0:11 offset1:10
	ds_read2_b32 v[62:63], v70 offset0:9 offset1:8
	ds_read2_b32 v[64:65], v70 offset0:3 offset1:2
	ds_read2_b32 v[66:67], v70 offset0:1 offset1:0
	s_waitcnt lgkmcnt(15)
	v_pk_add_f32 v[36:37], v[36:37], v[138:139] op_sel_hi:[1,0] neg_lo:[0,1] neg_hi:[0,1]
	s_waitcnt lgkmcnt(14)
	v_pk_add_f32 v[38:39], v[38:39], v[138:139] op_sel_hi:[1,0] neg_lo:[0,1] neg_hi:[0,1]
	s_waitcnt lgkmcnt(13)
	v_pk_add_f32 v[40:41], v[40:41], v[138:139] op_sel_hi:[1,0] neg_lo:[0,1] neg_hi:[0,1]
	s_waitcnt lgkmcnt(12)
	v_pk_add_f32 v[42:43], v[42:43], v[138:139] op_sel_hi:[1,0] neg_lo:[0,1] neg_hi:[0,1]
	s_waitcnt lgkmcnt(11)
	v_pk_add_f32 v[44:45], v[44:45], v[138:139] op_sel_hi:[1,0] neg_lo:[0,1] neg_hi:[0,1]
	s_waitcnt lgkmcnt(10)
	v_pk_add_f32 v[46:47], v[46:47], v[138:139] op_sel_hi:[1,0] neg_lo:[0,1] neg_hi:[0,1]
	s_waitcnt lgkmcnt(9)
	v_pk_add_f32 v[48:49], v[48:49], v[138:139] op_sel_hi:[1,0] neg_lo:[0,1] neg_hi:[0,1]
	s_waitcnt lgkmcnt(8)
	v_pk_add_f32 v[50:51], v[50:51], v[138:139] op_sel_hi:[1,0] neg_lo:[0,1] neg_hi:[0,1]
	s_waitcnt lgkmcnt(7)
	v_pk_add_f32 v[52:53], v[52:53], v[138:139] op_sel_hi:[1,0] neg_lo:[0,1] neg_hi:[0,1]
	s_waitcnt lgkmcnt(6)
	v_pk_add_f32 v[54:55], v[54:55], v[138:139] op_sel_hi:[1,0] neg_lo:[0,1] neg_hi:[0,1]
	s_waitcnt lgkmcnt(5)
	v_pk_add_f32 v[56:57], v[56:57], v[138:139] op_sel_hi:[1,0] neg_lo:[0,1] neg_hi:[0,1]
	s_waitcnt lgkmcnt(4)
	v_pk_add_f32 v[58:59], v[58:59], v[138:139] op_sel_hi:[1,0] neg_lo:[0,1] neg_hi:[0,1]
	s_waitcnt lgkmcnt(3)
	v_pk_add_f32 v[60:61], v[60:61], v[138:139] op_sel_hi:[1,0] neg_lo:[0,1] neg_hi:[0,1]
	s_waitcnt lgkmcnt(2)
	v_pk_add_f32 v[62:63], v[62:63], v[138:139] op_sel_hi:[1,0] neg_lo:[0,1] neg_hi:[0,1]
	s_waitcnt lgkmcnt(1)
	v_pk_add_f32 v[64:65], v[64:65], v[138:139] op_sel_hi:[1,0] neg_lo:[0,1] neg_hi:[0,1]
	s_waitcnt lgkmcnt(0)
	v_pk_add_f32 v[66:67], v[66:67], v[138:139] op_sel_hi:[1,0] neg_lo:[0,1] neg_hi:[0,1]
	v_mfma_f32_32x32x16_bf16 v[36:51], v[120:123], v[72:75], v[36:51]
	s_nop 0
	v_mfma_f32_32x32x16_bf16 v[52:67], v[146:149], v[72:75], v[52:67]
	v_mfma_f32_32x32x16_bf16 v[36:51], v[124:127], v[76:79], v[36:51]
	ds_read_b64_tr_b16 v[124:125], v129 offset:55296
	ds_read_b64_tr_b16 v[126:127], v129 offset:57856
	ds_read_b64_tr_b16 v[122:123], v129 offset:57920
	ds_read_b64_tr_b16 v[120:121], v129 offset:55360
	v_mfma_f32_32x32x16_bf16 v[52:67], v[150:153], v[76:79], v[52:67]
	v_mfma_f32_32x32x16_bf16 v[36:51], v[154:157], v[80:83], v[36:51]
	v_mfma_f32_32x32x16_bf16 v[52:67], v[162:165], v[80:83], v[52:67]
	v_mfma_f32_32x32x16_bf16 v[36:51], v[158:161], v[84:87], v[36:51]
	v_mfma_f32_32x32x16_bf16 v[52:67], v[166:169], v[84:87], v[52:67]
	s_nop 11
	v_max_f32_e32 v68, v36, v52
	v_max3_f32 v68, v68, v37, v38
	v_max3_f32 v68, v68, v39, v40
	v_max3_f32 v68, v68, v41, v42
	v_max3_f32 v68, v68, v43, v44
	v_max3_f32 v68, v68, v45, v46
	v_max3_f32 v68, v68, v47, v48
	v_max3_f32 v68, v68, v49, v50
	v_max3_f32 v68, v68, v51, v53
	v_max3_f32 v68, v68, v54, v55
	v_max3_f32 v68, v68, v56, v57
	v_max3_f32 v68, v68, v58, v59
	v_max3_f32 v68, v68, v60, v61
	v_max3_f32 v68, v68, v62, v63
	v_max3_f32 v68, v68, v64, v65
	v_max3_f32 v68, v68, v66, v67
	v_mov_b32_e32 v70, v68
	s_nop 1
	v_permlane32_swap_b32_e32 v68, v70
	v_max_f32_e32 v70, v68, v70
	s_and_b64 vcc, exec, s[38:39]
	s_cbranch_vccz .LBB9_76
	v_cmp_lt_f32_e32 vcc, s57, v70
	s_mov_b64 s[40:41], 0
	s_mov_b64 s[38:39], 0
	s_cbranch_vccz .LBB9_63
	v_max_f32_e32 v68, 0, v70
	s_mov_b64 s[38:39], -1

.LBB9_129:
	s_add_i32 s70, s66, s69
	s_cmp_le_i32 s70, s43
	s_cselect_b64 s[36:37], -1, 0
	s_and_b64 s[36:37], s[2:3], s[36:37]
	s_cmp_ge_i32 s70, s44
	s_cselect_b64 s[38:39], -1, 0
	s_and_b64 s[36:37], s[36:37], s[38:39]
	s_andn2_b64 vcc, exec, s[36:37]
	s_cbranch_vccnz .LBB9_138
	v_add_u32_e32 v36, v35, v128
	v_add_u32_e32 v66, s45, v144
	ds_read_b128 v[120:123], v36
	ds_read_b128 v[124:127], v36 offset:32
	ds_read_b128 v[146:149], v36 offset:8704
	ds_read_b128 v[150:153], v36 offset:8736
	ds_read_b128 v[154:157], v36 offset:64
	ds_read_b128 v[158:161], v36 offset:96
	ds_read_b128 v[162:165], v36 offset:8768
	ds_read_b128 v[166:169], v36 offset:8800
	v_add_u32_e32 v70, 0x12c10, v66
	ds_read2_b32 v[36:37], v70 offset0:59 offset1:58
	ds_read2_b32 v[38:39], v70 offset0:57 offset1:56
	ds_read2_b32 v[40:41], v70 offset0:51 offset1:50
	ds_read2_b32 v[42:43], v70 offset0:49 offset1:48
	ds_read2_b32 v[44:45], v70 offset0:43 offset1:42
	ds_read2_b32 v[46:47], v70 offset0:41 offset1:40
	ds_read2_b32 v[48:49], v70 offset0:35 offset1:34
	ds_read2_b32 v[50:51], v70 offset0:33 offset1:32
	ds_read2_b32 v[52:53], v70 offset0:27 offset1:26
	ds_read2_b32 v[54:55], v70 offset0:25 offset1:24
	ds_read2_b32 v[56:57], v70 offset0:19 offset1:18
	ds_read2_b32 v[58:59], v70 offset0:17 offset1:16
	ds_read2_b32 v[60:61], v70 offset0:11 offset1:10
	ds_read2_b32 v[62:63], v70 offset0:9 offset1:8
	ds_read2_b32 v[64:65], v70 offset0:3 offset1:2
	ds_read2_b32 v[66:67], v70 offset0:1 offset1:0
	s_waitcnt lgkmcnt(15)
	v_pk_add_f32 v[36:37], v[36:37], v[138:139] op_sel_hi:[1,0] neg_lo:[0,1] neg_hi:[0,1]
	s_waitcnt lgkmcnt(14)
	v_pk_add_f32 v[38:39], v[38:39], v[138:139] op_sel_hi:[1,0] neg_lo:[0,1] neg_hi:[0,1]
	s_waitcnt lgkmcnt(13)
	v_pk_add_f32 v[40:41], v[40:41], v[138:139] op_sel_hi:[1,0] neg_lo:[0,1] neg_hi:[0,1]
	s_waitcnt lgkmcnt(12)
	v_pk_add_f32 v[42:43], v[42:43], v[138:139] op_sel_hi:[1,0] neg_lo:[0,1] neg_hi:[0,1]
	s_waitcnt lgkmcnt(11)
	v_pk_add_f32 v[44:45], v[44:45], v[138:139] op_sel_hi:[1,0] neg_lo:[0,1] neg_hi:[0,1]
	s_waitcnt lgkmcnt(10)
	v_pk_add_f32 v[46:47], v[46:47], v[138:139] op_sel_hi:[1,0] neg_lo:[0,1] neg_hi:[0,1]
	s_waitcnt lgkmcnt(9)
	v_pk_add_f32 v[48:49], v[48:49], v[138:139] op_sel_hi:[1,0] neg_lo:[0,1] neg_hi:[0,1]
	s_waitcnt lgkmcnt(8)
	v_pk_add_f32 v[50:51], v[50:51], v[138:139] op_sel_hi:[1,0] neg_lo:[0,1] neg_hi:[0,1]
	s_waitcnt lgkmcnt(7)
	v_pk_add_f32 v[52:53], v[52:53], v[138:139] op_sel_hi:[1,0] neg_lo:[0,1] neg_hi:[0,1]
	s_waitcnt lgkmcnt(6)
	v_pk_add_f32 v[54:55], v[54:55], v[138:139] op_sel_hi:[1,0] neg_lo:[0,1] neg_hi:[0,1]
	s_waitcnt lgkmcnt(5)
	v_pk_add_f32 v[56:57], v[56:57], v[138:139] op_sel_hi:[1,0] neg_lo:[0,1] neg_hi:[0,1]
	s_waitcnt lgkmcnt(4)
	v_pk_add_f32 v[58:59], v[58:59], v[138:139] op_sel_hi:[1,0] neg_lo:[0,1] neg_hi:[0,1]
	s_waitcnt lgkmcnt(3)
	v_pk_add_f32 v[60:61], v[60:61], v[138:139] op_sel_hi:[1,0] neg_lo:[0,1] neg_hi:[0,1]
	s_waitcnt lgkmcnt(2)
	v_pk_add_f32 v[62:63], v[62:63], v[138:139] op_sel_hi:[1,0] neg_lo:[0,1] neg_hi:[0,1]
	s_waitcnt lgkmcnt(1)
	v_pk_add_f32 v[64:65], v[64:65], v[138:139] op_sel_hi:[1,0] neg_lo:[0,1] neg_hi:[0,1]
	s_waitcnt lgkmcnt(0)
	v_pk_add_f32 v[66:67], v[66:67], v[138:139] op_sel_hi:[1,0] neg_lo:[0,1] neg_hi:[0,1]
	s_xor_b64 s[36:37], s[10:11], -1
	v_mfma_f32_32x32x16_bf16 v[36:51], v[120:123], v[72:75], v[36:51]
	v_mfma_f32_32x32x16_bf16 v[52:67], v[146:149], v[72:75], v[52:67]
	v_mfma_f32_32x32x16_bf16 v[36:51], v[124:127], v[76:79], v[36:51]
	ds_read_b64_tr_b16 v[124:125], v129 offset:34816
	ds_read_b64_tr_b16 v[126:127], v129 offset:37376
	ds_read_b64_tr_b16 v[122:123], v129 offset:37440
	ds_read_b64_tr_b16 v[120:121], v129 offset:34880
	v_mfma_f32_32x32x16_bf16 v[52:67], v[150:153], v[76:79], v[52:67]
	v_mfma_f32_32x32x16_bf16 v[36:51], v[154:157], v[80:83], v[36:51]
	v_mfma_f32_32x32x16_bf16 v[52:67], v[162:165], v[80:83], v[52:67]
	v_mfma_f32_32x32x16_bf16 v[36:51], v[158:161], v[84:87], v[36:51]
	v_mfma_f32_32x32x16_bf16 v[52:67], v[166:169], v[84:87], v[52:67]
	s_nop 11
	v_max_f32_e32 v68, v36, v52
	v_max3_f32 v68, v68, v37, v38
	v_max3_f32 v68, v68, v39, v40
	v_max3_f32 v68, v68, v41, v42
	v_max3_f32 v68, v68, v43, v44
	v_max3_f32 v68, v68, v45, v46
	v_max3_f32 v68, v68, v47, v48
	v_max3_f32 v68, v68, v49, v50
	v_max3_f32 v68, v68, v51, v53
	v_max3_f32 v68, v68, v54, v55
	v_max3_f32 v68, v68, v56, v57
	v_max3_f32 v68, v68, v58, v59
	v_max3_f32 v68, v68, v60, v61
	v_max3_f32 v68, v68, v62, v63
	v_max3_f32 v68, v68, v64, v65
	v_max3_f32 v68, v68, v66, v67
	v_mov_b32_e32 v70, v68
	s_nop 1
	v_permlane32_swap_b32_e32 v68, v70
	v_max_f32_e32 v70, v68, v70
	s_and_b64 vcc, exec, s[36:37]
	s_cbranch_vccz .LBB9_164
	v_cmp_lt_f32_e32 vcc, s59, v70
	s_mov_b64 s[38:39], 0
	s_mov_b64 s[36:37], 0
	s_cbranch_vccz .LBB9_133
	v_max_f32_e32 v68, 0, v70
	s_mov_b64 s[36:37], -1

.LBB9_148:
	s_add_i32 s70, s70, 1
	s_cmp_le_i32 s70, s43
	s_cselect_b64 s[38:39], -1, 0
	s_and_b64 s[38:39], s[2:3], s[38:39]
	s_cmp_ge_i32 s70, s44
	s_cselect_b64 s[70:71], -1, 0
	s_and_b64 s[38:39], s[38:39], s[70:71]
	s_andn2_b64 vcc, exec, s[38:39]
	s_cbranch_vccnz .LBB9_157
	v_add_u32_e32 v36, v35, v128
	v_add_u32_e32 v66, s65, v143
	ds_read_b128 v[120:123], v36 offset:17408
	ds_read_b128 v[124:127], v36 offset:17440
	ds_read_b128 v[146:149], v36 offset:26112
	ds_read_b128 v[150:153], v36 offset:26144
	ds_read_b128 v[154:157], v36 offset:17472
	ds_read_b128 v[158:161], v36 offset:17504
	ds_read_b128 v[162:165], v36 offset:26176
	ds_read_b128 v[166:169], v36 offset:26208
	v_add_u32_e32 v70, 0x12b10, v66
	ds_read2_b32 v[36:37], v70 offset0:59 offset1:58
	ds_read2_b32 v[38:39], v70 offset0:57 offset1:56
	ds_read2_b32 v[40:41], v70 offset0:51 offset1:50
	ds_read2_b32 v[42:43], v70 offset0:49 offset1:48
	ds_read2_b32 v[44:45], v70 offset0:43 offset1:42
	ds_read2_b32 v[46:47], v70 offset0:41 offset1:40
	ds_read2_b32 v[48:49], v70 offset0:35 offset1:34
	ds_read2_b32 v[50:51], v70 offset0:33 offset1:32
	ds_read2_b32 v[52:53], v70 offset0:27 offset1:26
	ds_read2_b32 v[54:55], v70 offset0:25 offset1:24
	ds_read2_b32 v[56:57], v70 offset0:19 offset1:18
	ds_read2_b32 v[58:59], v70 offset0:17 offset1:16
	ds_read2_b32 v[60:61], v70 offset0:11 offset1:10
	ds_read2_b32 v[62:63], v70 offset0:9 offset1:8
	ds_read2_b32 v[64:65], v70 offset0:3 offset1:2
	ds_read2_b32 v[66:67], v70 offset0:1 offset1:0
	s_waitcnt lgkmcnt(15)
	v_pk_add_f32 v[36:37], v[36:37], v[138:139] op_sel_hi:[1,0] neg_lo:[0,1] neg_hi:[0,1]
	s_waitcnt lgkmcnt(14)
	v_pk_add_f32 v[38:39], v[38:39], v[138:139] op_sel_hi:[1,0] neg_lo:[0,1] neg_hi:[0,1]
	s_waitcnt lgkmcnt(13)
	v_pk_add_f32 v[40:41], v[40:41], v[138:139] op_sel_hi:[1,0] neg_lo:[0,1] neg_hi:[0,1]
	s_waitcnt lgkmcnt(12)
	v_pk_add_f32 v[42:43], v[42:43], v[138:139] op_sel_hi:[1,0] neg_lo:[0,1] neg_hi:[0,1]
	s_waitcnt lgkmcnt(11)
	v_pk_add_f32 v[44:45], v[44:45], v[138:139] op_sel_hi:[1,0] neg_lo:[0,1] neg_hi:[0,1]
	s_waitcnt lgkmcnt(10)
	v_pk_add_f32 v[46:47], v[46:47], v[138:139] op_sel_hi:[1,0] neg_lo:[0,1] neg_hi:[0,1]
	s_waitcnt lgkmcnt(9)
	v_pk_add_f32 v[48:49], v[48:49], v[138:139] op_sel_hi:[1,0] neg_lo:[0,1] neg_hi:[0,1]
	s_waitcnt lgkmcnt(8)
	v_pk_add_f32 v[50:51], v[50:51], v[138:139] op_sel_hi:[1,0] neg_lo:[0,1] neg_hi:[0,1]
	s_waitcnt lgkmcnt(7)
	v_pk_add_f32 v[52:53], v[52:53], v[138:139] op_sel_hi:[1,0] neg_lo:[0,1] neg_hi:[0,1]
	s_waitcnt lgkmcnt(6)
	v_pk_add_f32 v[54:55], v[54:55], v[138:139] op_sel_hi:[1,0] neg_lo:[0,1] neg_hi:[0,1]
	s_waitcnt lgkmcnt(5)
	v_pk_add_f32 v[56:57], v[56:57], v[138:139] op_sel_hi:[1,0] neg_lo:[0,1] neg_hi:[0,1]
	s_waitcnt lgkmcnt(4)
	v_pk_add_f32 v[58:59], v[58:59], v[138:139] op_sel_hi:[1,0] neg_lo:[0,1] neg_hi:[0,1]
	s_waitcnt lgkmcnt(3)
	v_pk_add_f32 v[60:61], v[60:61], v[138:139] op_sel_hi:[1,0] neg_lo:[0,1] neg_hi:[0,1]
	s_waitcnt lgkmcnt(2)
	v_pk_add_f32 v[62:63], v[62:63], v[138:139] op_sel_hi:[1,0] neg_lo:[0,1] neg_hi:[0,1]
	s_waitcnt lgkmcnt(1)
	v_pk_add_f32 v[64:65], v[64:65], v[138:139] op_sel_hi:[1,0] neg_lo:[0,1] neg_hi:[0,1]
	s_waitcnt lgkmcnt(0)
	v_pk_add_f32 v[66:67], v[66:67], v[138:139] op_sel_hi:[1,0] neg_lo:[0,1] neg_hi:[0,1]
	v_mfma_f32_32x32x16_bf16 v[36:51], v[120:123], v[72:75], v[36:51]
	s_nop 0
	v_mfma_f32_32x32x16_bf16 v[52:67], v[146:149], v[72:75], v[52:67]
	v_mfma_f32_32x32x16_bf16 v[36:51], v[124:127], v[76:79], v[36:51]
	ds_read_b64_tr_b16 v[124:125], v129 offset:55296
	ds_read_b64_tr_b16 v[126:127], v129 offset:57856
	ds_read_b64_tr_b16 v[122:123], v129 offset:57920
	ds_read_b64_tr_b16 v[120:121], v129 offset:55360
	v_mfma_f32_32x32x16_bf16 v[52:67], v[150:153], v[76:79], v[52:67]
	v_mfma_f32_32x32x16_bf16 v[36:51], v[154:157], v[80:83], v[36:51]
	v_mfma_f32_32x32x16_bf16 v[52:67], v[162:165], v[80:83], v[52:67]
	v_mfma_f32_32x32x16_bf16 v[36:51], v[158:161], v[84:87], v[36:51]
	v_mfma_f32_32x32x16_bf16 v[52:67], v[166:169], v[84:87], v[52:67]
	s_nop 11
	v_max_f32_e32 v68, v36, v52
	v_max3_f32 v68, v68, v37, v38
	v_max3_f32 v68, v68, v39, v40
	v_max3_f32 v68, v68, v41, v42
	v_max3_f32 v68, v68, v43, v44
	v_max3_f32 v68, v68, v45, v46
	v_max3_f32 v68, v68, v47, v48
	v_max3_f32 v68, v68, v49, v50
	v_max3_f32 v68, v68, v51, v53
	v_max3_f32 v68, v68, v54, v55
	v_max3_f32 v68, v68, v56, v57
	v_max3_f32 v68, v68, v58, v59
	v_max3_f32 v68, v68, v60, v61
	v_max3_f32 v68, v68, v62, v63
	v_max3_f32 v68, v68, v64, v65
	v_max3_f32 v68, v68, v66, v67
	v_mov_b32_e32 v70, v68
	s_nop 1
	v_permlane32_swap_b32_e32 v68, v70
	v_max_f32_e32 v70, v68, v70
	s_and_b64 vcc, exec, s[36:37]
	s_cbranch_vccz .LBB9_165
	v_cmp_lt_f32_e32 vcc, s59, v70
	s_mov_b64 s[38:39], 0
	s_mov_b64 s[36:37], 0
	s_cbranch_vccz .LBB9_152
	v_max_f32_e32 v68, 0, v70
	s_mov_b64 s[36:37], -1
